# MoBA general item: the 8 bias-table LDS lookups of each 64-key segment issued together (distinct registers, counted lgkmcnt) instead of 8 serialized round trips
# baseline (speedup 1.0000x reference)
; #define SBAR() __builtin_amdgcn_sched_barrier(0)
; #define SBAR() __builtin_amdgcn_sched_barrier(0)
; template <bool OWN>
; __device__ __forceinline__ void moba_item(const bf16x8 q0, const bf16x8 q1, LAS unsigned char* lds, int lane, int qb, int n, int qid, bool valid, int smax) {
;     ...
;     for (int sp = 0; sp < 4; ++sp) if (!OWN || 2 * sp <= smax) {
;         float tv[16];
; #pragma unroll
;         for (int t = 0; t < 4; ++t)
; #pragma unroll
;             for (int jj = 0; jj < 4; ++jj) tv[4 * t + jj] = tb[255 - (64 * sp + 32 * (t >> 1) + 16 * (t & 1) + jj)];
;         SBAR();
; #pragma unroll
;         for (int t = 0; t < 4; ++t)
; #pragma unroll
;             for (int jj = 0; jj < 4; ++jj) {
;                 float v = S[4 * sp + t][jj] * c2 + tv[4 * t + jj];
;                 if (OWN) { const int key = 64 * sp + 32 * (t >> 1) + 16 * (t & 1) + 4 * g + jj; v = (key <= qid) ? v : NEGF; }
;                 S[4 * sp + t][jj] = v; mx = fmaxf(mx, v);
;             }
;     }
.LBB0_514:
	s_waitcnt vmcnt(1)
	v_cndmask_b32_e64 v97, 0, 1, s[42:43]
	v_lshl_add_u32 v96, v222, 2, 0
	v_cmp_ne_u32_e64 s[40:41], 1, v97
	s_andn2_b64 vcc, exec, s[42:43]
	v_mov_b32_e32 v97, 0xf149f2ca
	s_cbranch_vccnz .LBB0_518
	v_add_u32_e32 v173, 0x1f34, v96
	ds_read2_b32 v[174:175], v173 offset0:50 offset1:51
	ds_read2_b32 v[176:177], v173 offset0:48 offset1:49
	ds_read2_b32 v[178:179], v173 offset0:34 offset1:35
	ds_read2_b32 v[180:181], v173 offset0:32 offset1:33
	ds_read2_b32 v[182:183], v173 offset0:18 offset1:19
	ds_read2_b32 v[184:185], v173 offset0:16 offset1:17
	ds_read2_b32 v[224:225], v173 offset0:2 offset1:3
	ds_read2_b32 v[226:227], v173 offset0:0 offset1:1
	v_cmp_ge_i32_e32 vcc, v221, v208
	s_waitcnt vmcnt(0)
	s_waitcnt lgkmcnt(7)
	v_fmamk_f32 v92, v92, 0x3e38aa3b, v175
	v_cndmask_b32_e32 v92, v237, v92, vcc
	v_fmac_f32_e32 v174, 0x3e38aa3b, v93
	v_cmp_gt_i32_e32 vcc, v221, v208
	s_nop 1
	v_cndmask_b32_e32 v93, v237, v174, vcc
	v_cmp_le_i32_e32 vcc, v107, v221
	v_max3_f32 v172, v92, s17, v93
	s_waitcnt lgkmcnt(6)
	v_pk_fma_f32 v[94:95], v[94:95], s[84:85], v[176:177] op_sel:[0,0,1] op_sel_hi:[1,0,0]
	v_cndmask_b32_e32 v95, v237, v95, vcc
	v_cmp_le_i32_e32 vcc, v106, v221
	s_waitcnt lgkmcnt(5)
	v_pk_fma_f32 v[88:89], v[88:89], s[84:85], v[178:179] op_sel:[0,0,1] op_sel_hi:[1,0,0]
	v_cndmask_b32_e32 v94, v237, v94, vcc
	v_cmp_le_i32_e32 vcc, v109, v221
	v_max3_f32 v97, v172, v94, v95
	s_waitcnt lgkmcnt(4)
	v_pk_fma_f32 v[90:91], v[90:91], s[84:85], v[180:181] op_sel:[0,0,1] op_sel_hi:[1,0,0]
	v_cndmask_b32_e32 v89, v237, v89, vcc
	v_cmp_le_i32_e32 vcc, v108, v221
	s_waitcnt lgkmcnt(3)
	v_pk_fma_f32 v[68:69], v[68:69], s[84:85], v[182:183] op_sel:[0,0,1] op_sel_hi:[1,0,0]
	v_cndmask_b32_e32 v88, v237, v88, vcc
	v_cmp_le_i32_e32 vcc, v111, v221
	v_max3_f32 v97, v97, v88, v89
	s_waitcnt lgkmcnt(2)
	v_pk_fma_f32 v[70:71], v[70:71], s[84:85], v[184:185] op_sel:[0,0,1] op_sel_hi:[1,0,0]
	v_cndmask_b32_e32 v91, v237, v91, vcc
	v_cmp_le_i32_e32 vcc, v110, v221
	s_waitcnt lgkmcnt(1)
	v_pk_fma_f32 v[64:65], v[64:65], s[84:85], v[224:225] op_sel:[0,0,1] op_sel_hi:[1,0,0]
	v_cndmask_b32_e32 v90, v237, v90, vcc
	v_cmp_le_i32_e32 vcc, v113, v221
	v_max3_f32 v97, v97, v90, v91
	s_nop 0
	v_cndmask_b32_e32 v69, v237, v69, vcc
	v_cmp_le_i32_e32 vcc, v112, v221
	s_nop 1
	v_cndmask_b32_e32 v68, v237, v68, vcc
	v_cmp_le_i32_e32 vcc, v115, v221
	v_max3_f32 v97, v97, v68, v69
	s_nop 0
	v_cndmask_b32_e32 v71, v237, v71, vcc
	v_cmp_le_i32_e32 vcc, v114, v221
	s_nop 1
	v_cndmask_b32_e32 v70, v237, v70, vcc
	v_cmp_le_i32_e32 vcc, v117, v221
	v_max3_f32 v97, v97, v70, v71
	s_nop 0
	v_cndmask_b32_e32 v65, v237, v65, vcc
	v_cmp_le_i32_e32 vcc, v116, v221
	s_nop 1
	v_cndmask_b32_e32 v64, v237, v64, vcc
	v_max3_f32 v97, v97, v64, v65
	s_waitcnt lgkmcnt(0)
	v_pk_fma_f32 v[66:67], v[66:67], s[84:85], v[226:227] op_sel:[0,0,1] op_sel_hi:[1,0,0]
	v_cmp_le_i32_e32 vcc, v119, v221
	s_nop 1
	v_cndmask_b32_e32 v67, v237, v67, vcc
	v_cmp_le_i32_e32 vcc, v118, v221
	s_nop 1
	v_cndmask_b32_e32 v66, v237, v66, vcc
	v_max3_f32 v97, v97, v66, v67
	v_cndmask_b32_e64 v98, 0, 1, s[44:45]
	v_cmp_ne_u32_e64 s[42:43], 1, v98
	s_andn2_b64 vcc, exec, s[44:45]
	s_cbranch_vccz .LBB0_519

; #define SBAR() __builtin_amdgcn_sched_barrier(0)
; #define SBAR() __builtin_amdgcn_sched_barrier(0)
; template <bool OWN>
; __device__ __forceinline__ void moba_item(const bf16x8 q0, const bf16x8 q1, LAS unsigned char* lds, int lane, int qb, int n, int qid, bool valid, int smax) {
;     ...
;     for (int sp = 0; sp < 4; ++sp) if (!OWN || 2 * sp <= smax) {
;         float tv[16];
; #pragma unroll
;         for (int t = 0; t < 4; ++t)
; #pragma unroll
;             for (int jj = 0; jj < 4; ++jj) tv[4 * t + jj] = tb[255 - (64 * sp + 32 * (t >> 1) + 16 * (t & 1) + jj)];
;         SBAR();
; #pragma unroll
;         for (int t = 0; t < 4; ++t)
; #pragma unroll
;             for (int jj = 0; jj < 4; ++jj) {
;                 float v = S[4 * sp + t][jj] * c2 + tv[4 * t + jj];
;                 if (OWN) { const int key = 64 * sp + 32 * (t >> 1) + 16 * (t & 1) + 4 * g + jj; v = (key <= qid) ? v : NEGF; }
;                 S[4 * sp + t][jj] = v; mx = fmaxf(mx, v);
;             }
;     }
.LBB0_517:
	v_add_u32_e32 v173, 0x1d34, v96
	ds_read2_b32 v[174:175], v173 offset0:50 offset1:51
	ds_read2_b32 v[176:177], v173 offset0:48 offset1:49
	ds_read2_b32 v[178:179], v173 offset0:34 offset1:35
	ds_read2_b32 v[180:181], v173 offset0:32 offset1:33
	ds_read2_b32 v[182:183], v173 offset0:18 offset1:19
	ds_read2_b32 v[184:185], v173 offset0:16 offset1:17
	ds_read2_b32 v[224:225], v173 offset0:2 offset1:3
	ds_read2_b32 v[226:227], v173 offset0:0 offset1:1
	s_waitcnt vmcnt(0)
	s_waitcnt lgkmcnt(7)
	v_pk_fma_f32 v[76:77], v[76:77], s[84:85], v[174:175] op_sel:[0,0,1] op_sel_hi:[1,0,0]
	v_cmp_le_i32_e32 vcc, v137, v221
	s_nop 1
	v_cndmask_b32_e32 v77, v237, v77, vcc
	s_waitcnt lgkmcnt(6)
	v_pk_fma_f32 v[78:79], v[78:79], s[84:85], v[176:177] op_sel:[0,0,1] op_sel_hi:[1,0,0]
	v_cmp_le_i32_e32 vcc, v138, v221
	s_waitcnt lgkmcnt(5)
	v_pk_fma_f32 v[72:73], v[72:73], s[84:85], v[178:179] op_sel:[0,0,1] op_sel_hi:[1,0,0]
	v_cndmask_b32_e32 v76, v237, v76, vcc
	v_cmp_le_i32_e32 vcc, v139, v221
	v_max3_f32 v97, v97, v76, v77
	s_waitcnt lgkmcnt(4)
	v_pk_fma_f32 v[74:75], v[74:75], s[84:85], v[180:181] op_sel:[0,0,1] op_sel_hi:[1,0,0]
	v_cndmask_b32_e32 v79, v237, v79, vcc
	v_cmp_le_i32_e32 vcc, v140, v221
	s_waitcnt lgkmcnt(3)
	v_pk_fma_f32 v[44:45], v[44:45], s[84:85], v[182:183] op_sel:[0,0,1] op_sel_hi:[1,0,0]
	v_cndmask_b32_e32 v78, v237, v78, vcc
	v_cmp_le_i32_e32 vcc, v141, v221
	v_max3_f32 v97, v97, v78, v79
	s_waitcnt lgkmcnt(2)
	v_pk_fma_f32 v[46:47], v[46:47], s[84:85], v[184:185] op_sel:[0,0,1] op_sel_hi:[1,0,0]
	v_cndmask_b32_e32 v73, v237, v73, vcc
	v_cmp_le_i32_e32 vcc, v142, v221
	s_waitcnt lgkmcnt(1)
	v_pk_fma_f32 v[40:41], v[40:41], s[84:85], v[224:225] op_sel:[0,0,1] op_sel_hi:[1,0,0]
	v_cndmask_b32_e32 v72, v237, v72, vcc
	v_cmp_le_i32_e32 vcc, v143, v221
	v_max3_f32 v97, v97, v72, v73
	s_nop 0
	v_cndmask_b32_e32 v75, v237, v75, vcc
	v_cmp_le_i32_e32 vcc, v144, v221
	s_nop 1
	v_cndmask_b32_e32 v74, v237, v74, vcc
	v_cmp_le_i32_e32 vcc, v145, v221
	v_max3_f32 v97, v97, v74, v75
	s_nop 0
	v_cndmask_b32_e32 v45, v237, v45, vcc
	v_cmp_le_i32_e32 vcc, v146, v221
	s_nop 1
	v_cndmask_b32_e32 v44, v237, v44, vcc
	v_cmp_le_i32_e32 vcc, v147, v221
	v_max3_f32 v97, v97, v44, v45
	s_nop 0
	v_cndmask_b32_e32 v47, v237, v47, vcc
	v_cmp_le_i32_e32 vcc, v148, v221
	s_nop 1
	v_cndmask_b32_e32 v46, v237, v46, vcc
	v_cmp_le_i32_e32 vcc, v149, v221
	v_max3_f32 v97, v97, v46, v47
	s_nop 0
	v_cndmask_b32_e32 v41, v237, v41, vcc
	v_cmp_le_i32_e32 vcc, v150, v221
	s_nop 1
	v_cndmask_b32_e32 v40, v237, v40, vcc
	v_max3_f32 v97, v97, v40, v41
	s_waitcnt lgkmcnt(0)
	v_pk_fma_f32 v[42:43], v[42:43], s[84:85], v[226:227] op_sel:[0,0,1] op_sel_hi:[1,0,0]
	v_cmp_le_i32_e32 vcc, v151, v221
	s_nop 1
	v_cndmask_b32_e32 v43, v237, v43, vcc
	v_cmp_le_i32_e32 vcc, v152, v221
	s_nop 1
	v_cndmask_b32_e32 v42, v237, v42, vcc
	v_max3_f32 v97, v97, v42, v43
	v_cndmask_b32_e64 v98, 0, 1, s[50:51]
	v_cmp_ne_u32_e64 s[46:47], 1, v98
	s_andn2_b64 vcc, exec, s[50:51]
	s_cbranch_vccz .LBB0_521
	s_branch .LBB0_522

; #define SBAR() __builtin_amdgcn_sched_barrier(0)
; #define SBAR() __builtin_amdgcn_sched_barrier(0)
; template <bool OWN>
; __device__ __forceinline__ void moba_item(const bf16x8 q0, const bf16x8 q1, LAS unsigned char* lds, int lane, int qb, int n, int qid, bool valid, int smax) {
;     ...
;     for (int sp = 0; sp < 4; ++sp) if (!OWN || 2 * sp <= smax) {
;         float tv[16];
; #pragma unroll
;         for (int t = 0; t < 4; ++t)
; #pragma unroll
;             for (int jj = 0; jj < 4; ++jj) tv[4 * t + jj] = tb[255 - (64 * sp + 32 * (t >> 1) + 16 * (t & 1) + jj)];
;         SBAR();
; #pragma unroll
;         for (int t = 0; t < 4; ++t)
; #pragma unroll
;             for (int jj = 0; jj < 4; ++jj) {
;                 float v = S[4 * sp + t][jj] * c2 + tv[4 * t + jj];
;                 if (OWN) { const int key = 64 * sp + 32 * (t >> 1) + 16 * (t & 1) + 4 * g + jj; v = (key <= qid) ? v : NEGF; }
;                 S[4 * sp + t][jj] = v; mx = fmaxf(mx, v);
;             }
;     }
.LBB0_519:
	v_add_u32_e32 v173, 0x1e34, v96
	ds_read2_b32 v[174:175], v173 offset0:50 offset1:51
	ds_read2_b32 v[176:177], v173 offset0:48 offset1:49
	ds_read2_b32 v[178:179], v173 offset0:34 offset1:35
	ds_read2_b32 v[180:181], v173 offset0:32 offset1:33
	ds_read2_b32 v[182:183], v173 offset0:18 offset1:19
	ds_read2_b32 v[184:185], v173 offset0:16 offset1:17
	ds_read2_b32 v[224:225], v173 offset0:2 offset1:3
	ds_read2_b32 v[226:227], v173 offset0:0 offset1:1
	s_waitcnt vmcnt(0)
	s_waitcnt lgkmcnt(7)
	v_pk_fma_f32 v[84:85], v[84:85], s[84:85], v[174:175] op_sel:[0,0,1] op_sel_hi:[1,0,0]
	v_cmp_le_i32_e32 vcc, v121, v221
	s_nop 1
	v_cndmask_b32_e32 v85, v237, v85, vcc
	s_waitcnt lgkmcnt(6)
	v_pk_fma_f32 v[86:87], v[86:87], s[84:85], v[176:177] op_sel:[0,0,1] op_sel_hi:[1,0,0]
	v_cmp_le_i32_e32 vcc, v120, v221
	s_waitcnt lgkmcnt(5)
	v_pk_fma_f32 v[80:81], v[80:81], s[84:85], v[178:179] op_sel:[0,0,1] op_sel_hi:[1,0,0]
	v_cndmask_b32_e32 v84, v237, v84, vcc
	v_cmp_le_i32_e32 vcc, v123, v221
	v_max3_f32 v97, v97, v84, v85
	s_waitcnt lgkmcnt(4)
	v_pk_fma_f32 v[82:83], v[82:83], s[84:85], v[180:181] op_sel:[0,0,1] op_sel_hi:[1,0,0]
	v_cndmask_b32_e32 v87, v237, v87, vcc
	v_cmp_le_i32_e32 vcc, v122, v221
	s_waitcnt lgkmcnt(3)
	v_pk_fma_f32 v[52:53], v[52:53], s[84:85], v[182:183] op_sel:[0,0,1] op_sel_hi:[1,0,0]
	v_cndmask_b32_e32 v86, v237, v86, vcc
	v_cmp_le_i32_e32 vcc, v125, v221
	v_max3_f32 v97, v97, v86, v87
	s_waitcnt lgkmcnt(2)
	v_pk_fma_f32 v[54:55], v[54:55], s[84:85], v[184:185] op_sel:[0,0,1] op_sel_hi:[1,0,0]
	v_cndmask_b32_e32 v81, v237, v81, vcc
	v_cmp_le_i32_e32 vcc, v124, v221
	s_waitcnt lgkmcnt(1)
	v_pk_fma_f32 v[48:49], v[48:49], s[84:85], v[224:225] op_sel:[0,0,1] op_sel_hi:[1,0,0]
	v_cndmask_b32_e32 v80, v237, v80, vcc
	v_cmp_le_i32_e32 vcc, v127, v221
	v_max3_f32 v97, v97, v80, v81
	s_nop 0
	v_cndmask_b32_e32 v83, v237, v83, vcc
	v_cmp_le_i32_e32 vcc, v126, v221
	s_nop 1
	v_cndmask_b32_e32 v82, v237, v82, vcc
	v_cmp_le_i32_e32 vcc, v129, v221
	v_max3_f32 v97, v97, v82, v83
	s_nop 0
	v_cndmask_b32_e32 v53, v237, v53, vcc
	v_cmp_le_i32_e32 vcc, v128, v221
	s_nop 1
	v_cndmask_b32_e32 v52, v237, v52, vcc
	v_cmp_le_i32_e32 vcc, v131, v221
	v_max3_f32 v97, v97, v52, v53
	s_nop 0
	v_cndmask_b32_e32 v55, v237, v55, vcc
	v_cmp_le_i32_e32 vcc, v130, v221
	s_nop 1
	v_cndmask_b32_e32 v54, v237, v54, vcc
	v_cmp_le_i32_e32 vcc, v133, v221
	v_max3_f32 v97, v97, v54, v55
	s_nop 0
	v_cndmask_b32_e32 v49, v237, v49, vcc
	v_cmp_le_i32_e32 vcc, v134, v221
	s_nop 1
	v_cndmask_b32_e32 v48, v237, v48, vcc
	v_max3_f32 v97, v97, v48, v49
	s_waitcnt lgkmcnt(0)
	v_pk_fma_f32 v[50:51], v[50:51], s[84:85], v[226:227] op_sel:[0,0,1] op_sel_hi:[1,0,0]
	v_cmp_le_i32_e32 vcc, v135, v221
	s_nop 1
	v_cndmask_b32_e32 v51, v237, v51, vcc
	v_cmp_le_i32_e32 vcc, v136, v221
	s_nop 1
	v_cndmask_b32_e32 v50, v237, v50, vcc
	v_max3_f32 v97, v97, v50, v51
	v_cndmask_b32_e64 v98, 0, 1, s[46:47]
	v_cmp_ne_u32_e64 s[44:45], 1, v98
	s_andn2_b64 vcc, exec, s[46:47]
	s_cbranch_vccz .LBB0_517

; #define SBAR() __builtin_amdgcn_sched_barrier(0)
; #define SBAR() __builtin_amdgcn_sched_barrier(0)
; template <bool OWN>
; __device__ __forceinline__ void moba_item(const bf16x8 q0, const bf16x8 q1, LAS unsigned char* lds, int lane, int qb, int n, int qid, bool valid, int smax) {
;     ...
;     for (int sp = 0; sp < 4; ++sp) if (!OWN || 2 * sp <= smax) {
;         float tv[16];
; #pragma unroll
;         for (int t = 0; t < 4; ++t)
; #pragma unroll
;             for (int jj = 0; jj < 4; ++jj) tv[4 * t + jj] = tb[255 - (64 * sp + 32 * (t >> 1) + 16 * (t & 1) + jj)];
;         SBAR();
; #pragma unroll
;         for (int t = 0; t < 4; ++t)
; #pragma unroll
;             for (int jj = 0; jj < 4; ++jj) {
;                 float v = S[4 * sp + t][jj] * c2 + tv[4 * t + jj];
;                 if (OWN) { const int key = 64 * sp + 32 * (t >> 1) + 16 * (t & 1) + 4 * g + jj; v = (key <= qid) ? v : NEGF; }
;                 S[4 * sp + t][jj] = v; mx = fmaxf(mx, v);
;             }
;     }
.LBB0_521:
	v_add_u32_e32 v173, 0x1c34, v96
	ds_read2_b32 v[174:175], v173 offset0:50 offset1:51
	ds_read2_b32 v[176:177], v173 offset0:48 offset1:49
	ds_read2_b32 v[178:179], v173 offset0:34 offset1:35
	ds_read2_b32 v[180:181], v173 offset0:32 offset1:33
	ds_read2_b32 v[182:183], v173 offset0:18 offset1:19
	ds_read2_b32 v[184:185], v173 offset0:16 offset1:17
	ds_read2_b32 v[224:225], v173 offset0:2 offset1:3
	ds_read2_b32 v[226:227], v173 offset0:0 offset1:1
	v_cmp_le_i32_e32 vcc, v153, v221
	s_waitcnt vmcnt(0)
	s_waitcnt lgkmcnt(7)
	v_pk_fma_f32 v[60:61], v[60:61], s[84:85], v[174:175] op_sel:[0,0,1] op_sel_hi:[1,0,0]
	v_cndmask_b32_e32 v61, v237, v61, vcc
	v_cmp_le_i32_e32 vcc, v154, v221
	s_nop 1
	v_cndmask_b32_e32 v60, v237, v60, vcc
	v_max3_f32 v98, v97, v60, v61
	v_cmp_le_i32_e32 vcc, v155, v221
	s_waitcnt lgkmcnt(6)
	v_pk_fma_f32 v[62:63], v[62:63], s[84:85], v[176:177] op_sel:[0,0,1] op_sel_hi:[1,0,0]
	v_cndmask_b32_e32 v63, v237, v63, vcc
	v_cmp_le_i32_e32 vcc, v156, v221
	s_waitcnt lgkmcnt(5)
	v_pk_fma_f32 v[56:57], v[56:57], s[84:85], v[178:179] op_sel:[0,0,1] op_sel_hi:[1,0,0]
	v_cndmask_b32_e32 v62, v237, v62, vcc
	v_cmp_le_i32_e32 vcc, v157, v221
	v_max3_f32 v98, v98, v62, v63
	s_waitcnt lgkmcnt(4)
	v_pk_fma_f32 v[58:59], v[58:59], s[84:85], v[180:181] op_sel:[0,0,1] op_sel_hi:[1,0,0]
	v_cndmask_b32_e32 v57, v237, v57, vcc
	v_cmp_le_i32_e32 vcc, v158, v221
	s_waitcnt lgkmcnt(3)
	v_pk_fma_f32 v[36:37], v[36:37], s[84:85], v[182:183] op_sel:[0,0,1] op_sel_hi:[1,0,0]
	v_cndmask_b32_e32 v56, v237, v56, vcc
	v_cmp_le_i32_e32 vcc, v159, v221
	v_max3_f32 v98, v98, v56, v57
	s_waitcnt lgkmcnt(2)
	v_pk_fma_f32 v[38:39], v[38:39], s[84:85], v[184:185] op_sel:[0,0,1] op_sel_hi:[1,0,0]
	v_cndmask_b32_e32 v59, v237, v59, vcc
	v_cmp_le_i32_e32 vcc, v160, v221
	s_waitcnt lgkmcnt(1)
	v_pk_fma_f32 v[32:33], v[32:33], s[84:85], v[224:225] op_sel:[0,0,1] op_sel_hi:[1,0,0]
	v_cndmask_b32_e32 v58, v237, v58, vcc
	v_cmp_le_i32_e32 vcc, v161, v221
	v_max3_f32 v98, v98, v58, v59
	s_nop 0
	v_cndmask_b32_e32 v37, v237, v37, vcc
	v_cmp_le_i32_e32 vcc, v162, v221
	s_nop 1
	v_cndmask_b32_e32 v36, v237, v36, vcc
	v_cmp_le_i32_e32 vcc, v163, v221
	v_max3_f32 v98, v98, v36, v37
	s_nop 0
	v_cndmask_b32_e32 v39, v237, v39, vcc
	v_cmp_le_i32_e32 vcc, v164, v221
	s_nop 1
	v_cndmask_b32_e32 v38, v237, v38, vcc
	v_cmp_le_i32_e32 vcc, v165, v221
	v_max3_f32 v98, v98, v38, v39
	s_nop 0
	v_cndmask_b32_e32 v33, v237, v33, vcc
	v_cmp_le_i32_e32 vcc, v166, v221
	s_nop 1
	v_cndmask_b32_e32 v32, v237, v32, vcc
	v_max3_f32 v98, v98, v32, v33
	s_waitcnt lgkmcnt(0)
	v_pk_fma_f32 v[34:35], v[34:35], s[84:85], v[226:227] op_sel:[0,0,1] op_sel_hi:[1,0,0]
	v_cmp_le_i32_e32 vcc, v167, v221
	s_nop 1
	v_cndmask_b32_e32 v35, v237, v35, vcc
	v_cmp_le_i32_e32 vcc, v168, v221
	s_nop 1
	v_cndmask_b32_e32 v34, v237, v34, vcc
	v_max3_f32 v97, v98, v34, v35
